# v5 + redundant acquire invalidate removed in the two fused-LayerNorm stat exchanges (slots are sc1 both sides)
# speedup vs baseline: 1.0074x; 1.0020x over previous
;     __device__ __forceinline__ void fused(Acc& acc, const Unit& u, int wr, int wc, int fr, int fq, LAS unsigned char* lds, int wid, int lane) const {
;     ...
;         if (wid == 0) {
;             unsigned sp = 0u;
;             while ((unsigned)__builtin_amdgcn_readfirstlane(__hip_atomic_load(cnt + 64 * u.pm, __ATOMIC_RELAXED, __HIP_MEMORY_SCOPE_AGENT)) < 64u) { __builtin_amdgcn_s_sleep(2); if (++sp > (1u << 22)) break; }
;             __builtin_amdgcn_fence(__ATOMIC_ACQUIRE, "agent");
;         }
;         asm volatile("s_waitcnt vmcnt(0) lgkmcnt(0)" ::: "memory"); __builtin_amdgcn_s_barrier(); asm volatile("" ::: "memory");
;         if (lane < 32) {
;             const unsigned long long* slot = slots + (size_t)(u.pm * 256 + rowi) * 8; float S = 0.f, SS = 0.f;
; #pragma unroll
;             for (int t = 0; t < 8; ++t) { const unsigned long long w = __hip_atomic_load(slot + t, __ATOMIC_RELAXED, __HIP_MEMORY_SCOPE_AGENT); S += __uint_as_float((unsigned)w); SS += __uint_as_float((unsigned)(w >> 32)); }
;             const float mean = S * (1.0f / DM), var = SS * (1.0f / DM) - mean * mean;
;             St[rowi] = (f32x2){mean, rsqrtf(var + 1e-5f)};
;         }
.LBB0_362:
.LBB0_363:
	s_waitcnt vmcnt(0) lgkmcnt(0)
	s_barrier
	s_and_saveexec_b64 s[6:7], s[4:5]
	s_cbranch_execz .LBB0_365
	v_lshlrev_b64 v[0:1], 6, v[0:1]
	v_lshl_add_u64 v[0:1], s[0:1], 0, v[0:1]
	global_load_dwordx2 v[4:5], v[0:1], off sc1
	global_load_dwordx2 v[6:7], v[0:1], off offset:8 sc1
	global_load_dwordx2 v[8:9], v[0:1], off offset:16 sc1
	global_load_dwordx2 v[10:11], v[0:1], off offset:24 sc1
	global_load_dwordx2 v[12:13], v[0:1], off offset:32 sc1
	global_load_dwordx2 v[14:15], v[0:1], off offset:40 sc1
	global_load_dwordx2 v[80:81], v[0:1], off offset:48 sc1
	s_nop 0
	global_load_dwordx2 v[0:1], v[0:1], off offset:56 sc1
	s_mov_b32 s0, 0x3a000000
	s_mov_b32 s1, 0x800000
	v_lshl_add_u32 v2, v2, 3, 0
	s_waitcnt vmcnt(7) lgkmcnt(0)
	v_add_f32_e32 v3, 0, v4
	s_waitcnt vmcnt(6)
	v_add_f32_e32 v3, v3, v6
	v_add_f32_e32 v4, 0, v5
	s_waitcnt vmcnt(5)
	v_add_f32_e32 v3, v3, v8
	v_add_f32_e32 v4, v4, v7
	s_waitcnt vmcnt(4)
	v_add_f32_e32 v3, v3, v10
	v_add_f32_e32 v4, v4, v9
	s_waitcnt vmcnt(3)
	v_add_f32_e32 v3, v3, v12
	v_add_f32_e32 v4, v4, v11
	s_waitcnt vmcnt(2)
	v_add_f32_e32 v3, v3, v14
	v_add_f32_e32 v4, v4, v13
	s_waitcnt vmcnt(1)
	v_add_f32_e32 v3, v3, v80
	v_add_f32_e32 v4, v4, v15
	s_waitcnt vmcnt(0)
	v_add_f32_e32 v0, v3, v0
	v_add_f32_e32 v4, v4, v81
	v_mul_f32_e32 v0, 0x3a000000, v0
	v_add_f32_e32 v1, v4, v1
	v_mul_f32_e32 v3, v0, v0
	v_fma_f32 v1, v1, s0, -v3
	v_add_f32_e32 v1, 0x3727c5ac, v1
	v_mul_f32_e32 v3, 0x4b800000, v1
	v_cmp_gt_f32_e32 vcc, s1, v1
	s_nop 1
	v_cndmask_b32_e32 v1, v1, v3, vcc
	v_rsq_f32_e32 v1, v1
	s_nop 0
	v_mul_f32_e32 v3, 0x45800000, v1
	v_cndmask_b32_e32 v1, v1, v3, vcc
	ds_write_b64 v2, v[0:1] offset:8192
